# residual epilogue software pipeline deepened from 4 to 5 row-blocks of loads in flight
# baseline (speedup 1.0000x reference)
; __device__ __forceinline__ unsigned cvtpk(float lo, float hi) { f32x2 v = {lo, hi}; bf16x2_t b = __builtin_convertvector(v, bf16x2_t); return __builtin_bit_cast(unsigned, b); }
;     __device__ __forceinline__ void operator()(const f32x4 (&acc)[2][2][4][2], const pg8::Unit& u, int wr, int wc, int fr, int fq) const {
;     ...
;         for (int ai = 0; ai < 2; ++ai)
; #pragma unroll
;             for (int m = 0; m < 4; ++m) {
;                 const int grow = row_base + u.pm * 256 + ai * 128 + wr * 64 + m * 16 + fr;
;                 const bool ok = grow < MREAL;
;                 float ss = 0.f;
;                 if (ok) {
;                     const float* src; float* dst;
;                     if (grow < ROWS_P) { src = srcA + (size_t)grow * DM; dst = dstMain + (size_t)grow * DM; }
;                     else if (grow < ROWS_MAIN) { src = srcB + (size_t)(grow - ROWS_P) * DM; dst = dstMain + (size_t)grow * DM; }
;                     else { const int mr = grow - ROWS_MAIN; src = srcM + (size_t)(mr & meta_mask) * DM; dst = dstM + (size_t)mr * DM; }
; #pragma unroll
;                     for (int bj = 0; bj < 2; ++bj) {
;                         const int col0 = u.pn * 256 + bj * 128 + wc * 32 + 8 * fq;
;                         const f32x4 h0 = *(const f32x4*)(src + col0) + acc[ai][bj][m][0];
;                         const f32x4 h1 = *(const f32x4*)(src + col0 + 4) + acc[ai][bj][m][1];
;                         *(f32x4*)(dst + col0) = h0; *(f32x4*)(dst + col0 + 4) = h1;
;                         if (P) { u32x4 w; w.x = cvtpk(h0[0], h0[1]); w.y = cvtpk(h0[2], h0[3]); w.z = cvtpk(h1[0], h1[1]); w.w = cvtpk(h1[2], h1[3]);
;                             *(u32x4*)(P + (size_t)grow * DM + col0) = w; }
;                         ss += (h0[0] * h0[0] + h0[1] * h0[1]) + (h0[2] * h0[2] + h0[3] * h0[3]) + (h1[0] * h1[0] + h1[1] * h1[1]) + (h1[2] * h1[2] + h1[3] * h1[3]);
;                     }
.LBB0_798:
	s_lshl_b32 vcc_lo, s42, 8
	s_cmp_lt_u32 vcc_lo, 0x18000
	s_cbranch_scc0 .Lepi_old_ao
	s_cmp_lg_u64 s[28:29], 0
	s_cbranch_scc0 .Lepi_old_ao
	s_cmp_lg_u64 s[30:31], 0
	s_cbranch_scc0 .Lepi_old_ao
	s_lshl_b32 vcc_hi, s8, 10
	s_lshl_b32 s8, vcc_lo, 3
	s_add_u32 s8, s16, s8
	s_addc_u32 s9, s17, 0
	s_lshl_b32 s6, vcc_lo, 12
	s_add_u32 vcc_hi, vcc_hi, s6
	s_add_u32 s44, s12, vcc_hi
	s_addc_u32 s45, s13, 0
	s_lshr_b32 s6, vcc_hi, 1
	s_add_u32 s6, s10, s6
	s_addc_u32 s7, s11, 0
	s_cmp_lt_u32 vcc_lo, 0x8000
	s_cselect_b32 s42, s24, s22
	s_cselect_b32 s43, s25, s23
	s_cselect_b32 vcc_lo, 0, 0x8000000
	s_sub_u32 vcc_hi, vcc_hi, vcc_lo
	s_add_u32 s42, s42, vcc_hi
	s_addc_u32 s43, s43, 0
	v_lshlrev_b32_e32 v150, 12, v164
	v_lshl_add_u32 v150, v166, 2, v150
	v_lshrrev_b32_e32 v151, 1, v150
	v_lshlrev_b32_e32 v162, 3, v164
	global_load_dwordx4 v[168:171], v150, s[42:43]
	global_load_dwordx4 v[172:175], v150, s[42:43] offset:16
	global_load_dwordx4 v[176:179], v150, s[42:43] offset:512
	global_load_dwordx4 v[180:183], v150, s[42:43] offset:528
	s_add_u32 s42, s42, 0x10000
	s_addc_u32 s43, s43, 0
	global_load_dwordx4 v[184:187], v150, s[42:43]
	global_load_dwordx4 v[188:191], v150, s[42:43] offset:16
	global_load_dwordx4 v[192:195], v150, s[42:43] offset:512
	global_load_dwordx4 v[196:199], v150, s[42:43] offset:528
	s_add_u32 s42, s42, 0x10000
	s_addc_u32 s43, s43, 0
	global_load_dwordx4 v[216:219], v150, s[42:43]
	global_load_dwordx4 v[220:223], v150, s[42:43] offset:16
	global_load_dwordx4 v[224:227], v150, s[42:43] offset:512
	global_load_dwordx4 v[228:231], v150, s[42:43] offset:528
	s_add_u32 s42, s42, 0x10000
	s_addc_u32 s43, s43, 0
	global_load_dwordx4 v[142:145], v150, s[42:43]
	global_load_dwordx4 v[146:149], v150, s[42:43] offset:16
	global_load_dwordx4 v[158:161], v150, s[42:43] offset:512
	global_load_dwordx4 v[204:207], v150, s[42:43] offset:528
	s_add_u32 s42, s42, 0x50000
	s_addc_u32 s43, s43, 0
	global_load_dwordx4 v[232:235], v150, s[42:43]
	global_load_dwordx4 v[236:239], v150, s[42:43] offset:16
	global_load_dwordx4 v[240:243], v150, s[42:43] offset:512
	global_load_dwordx4 v[248:251], v150, s[42:43] offset:528
	s_add_u32 s42, s42, 0x10000
	s_addc_u32 s43, s43, 0
	s_waitcnt vmcnt(16)
	v_pk_add_f32 v[126:127], v[126:127], v[168:169]
	v_pk_add_f32 v[128:129], v[128:129], v[170:171]
	v_pk_add_f32 v[122:123], v[122:123], v[172:173]
	v_pk_add_f32 v[124:125], v[124:125], v[174:175]
	v_pk_add_f32 v[118:119], v[118:119], v[176:177]
	v_pk_add_f32 v[120:121], v[120:121], v[178:179]
	v_pk_add_f32 v[114:115], v[114:115], v[180:181]
	v_pk_add_f32 v[116:117], v[116:117], v[182:183]
	global_store_dwordx4 v150, v[126:129], s[44:45]
	global_store_dwordx4 v150, v[122:125], s[44:45] offset:16
	global_store_dwordx4 v150, v[118:121], s[44:45] offset:512
	global_store_dwordx4 v150, v[114:117], s[44:45] offset:528
	v_cvt_pk_bf16_f32 v168, v126, v127
	v_cvt_pk_bf16_f32 v169, v128, v129
	v_cvt_pk_bf16_f32 v170, v122, v123
	v_cvt_pk_bf16_f32 v171, v124, v125
	v_cvt_pk_bf16_f32 v172, v118, v119
	v_cvt_pk_bf16_f32 v173, v120, v121
	v_cvt_pk_bf16_f32 v174, v114, v115
	v_cvt_pk_bf16_f32 v175, v116, v117
	global_store_dwordx4 v151, v[168:171], s[6:7]
	global_store_dwordx4 v151, v[172:175], s[6:7] offset:256
	v_mul_f32_e32 v163, v126, v126
	v_mul_f32_e32 v200, v127, v127
	v_fmac_f32_e32 v163, v128, v128
	v_fmac_f32_e32 v200, v129, v129
	v_fmac_f32_e32 v163, v122, v122
	v_fmac_f32_e32 v200, v123, v123
	v_fmac_f32_e32 v163, v124, v124
	v_fmac_f32_e32 v200, v125, v125
	v_fmac_f32_e32 v163, v118, v118
	v_fmac_f32_e32 v200, v119, v119
	v_fmac_f32_e32 v163, v120, v120
	v_fmac_f32_e32 v200, v121, v121
	v_fmac_f32_e32 v163, v114, v114
	v_fmac_f32_e32 v200, v115, v115
	v_fmac_f32_e32 v163, v116, v116
	v_fmac_f32_e32 v200, v117, v117
	v_add_f32_e32 v114, v163, v200
	s_add_u32 s44, s44, 0x10000
	s_addc_u32 s45, s45, 0
	s_add_u32 s6, s6, 0x8000
	s_addc_u32 s7, s7, 0
	global_load_dwordx4 v[168:171], v150, s[42:43]
	global_load_dwordx4 v[172:175], v150, s[42:43] offset:16
	global_load_dwordx4 v[176:179], v150, s[42:43] offset:512
	global_load_dwordx4 v[180:183], v150, s[42:43] offset:528
	s_add_u32 s42, s42, 0x10000
	s_addc_u32 s43, s43, 0
	s_waitcnt vmcnt(22)
	v_pk_add_f32 v[110:111], v[110:111], v[184:185]
	v_pk_add_f32 v[112:113], v[112:113], v[186:187]
	v_pk_add_f32 v[106:107], v[106:107], v[188:189]
	v_pk_add_f32 v[108:109], v[108:109], v[190:191]
	v_pk_add_f32 v[102:103], v[102:103], v[192:193]
	v_pk_add_f32 v[104:105], v[104:105], v[194:195]
	v_pk_add_f32 v[98:99], v[98:99], v[196:197]
	v_pk_add_f32 v[100:101], v[100:101], v[198:199]
	global_store_dwordx4 v150, v[110:113], s[44:45]
	global_store_dwordx4 v150, v[106:109], s[44:45] offset:16
	global_store_dwordx4 v150, v[102:105], s[44:45] offset:512
	global_store_dwordx4 v150, v[98:101], s[44:45] offset:528
	v_cvt_pk_bf16_f32 v184, v110, v111
	v_cvt_pk_bf16_f32 v185, v112, v113
	v_cvt_pk_bf16_f32 v186, v106, v107
	v_cvt_pk_bf16_f32 v187, v108, v109
	v_cvt_pk_bf16_f32 v188, v102, v103
	v_cvt_pk_bf16_f32 v189, v104, v105
	v_cvt_pk_bf16_f32 v190, v98, v99
	v_cvt_pk_bf16_f32 v191, v100, v101
	global_store_dwordx4 v151, v[184:187], s[6:7]
	global_store_dwordx4 v151, v[188:191], s[6:7] offset:256
	v_mul_f32_e32 v163, v110, v110
	v_mul_f32_e32 v200, v111, v111
	v_fmac_f32_e32 v163, v112, v112
	v_fmac_f32_e32 v200, v113, v113
	v_fmac_f32_e32 v163, v106, v106
	v_fmac_f32_e32 v200, v107, v107
	v_fmac_f32_e32 v163, v108, v108
	v_fmac_f32_e32 v200, v109, v109
	v_fmac_f32_e32 v163, v102, v102
	v_fmac_f32_e32 v200, v103, v103
	v_fmac_f32_e32 v163, v104, v104
	v_fmac_f32_e32 v200, v105, v105
	v_fmac_f32_e32 v163, v98, v98
	v_fmac_f32_e32 v200, v99, v99
	v_fmac_f32_e32 v163, v100, v100
	v_fmac_f32_e32 v200, v101, v101
	v_add_f32_e32 v98, v163, v200
	s_add_u32 s44, s44, 0x10000
	s_addc_u32 s45, s45, 0
	s_add_u32 s6, s6, 0x8000
	s_addc_u32 s7, s7, 0
	global_load_dwordx4 v[184:187], v150, s[42:43]
	global_load_dwordx4 v[188:191], v150, s[42:43] offset:16
	global_load_dwordx4 v[192:195], v150, s[42:43] offset:512
	global_load_dwordx4 v[196:199], v150, s[42:43] offset:528
	s_add_u32 s42, s42, 0x10000
	s_addc_u32 s43, s43, 0
	s_waitcnt vmcnt(28)
; __device__ __forceinline__ unsigned cvtpk(float lo, float hi) { f32x2 v = {lo, hi}; bf16x2_t b = __builtin_convertvector(v, bf16x2_t); return __builtin_bit_cast(unsigned, b); }
;     __device__ __forceinline__ void operator()(const f32x4 (&acc)[2][2][4][2], const pg8::Unit& u, int wr, int wc, int fr, int fq) const {
;     ...
; #pragma unroll
;                     for (int bj = 0; bj < 2; ++bj) {
;                         const int col0 = u.pn * 256 + bj * 128 + wc * 32 + 8 * fq;
;                         const f32x4 h0 = *(const f32x4*)(src + col0) + acc[ai][bj][m][0];
;                         const f32x4 h1 = *(const f32x4*)(src + col0 + 4) + acc[ai][bj][m][1];
;                         *(f32x4*)(dst + col0) = h0; *(f32x4*)(dst + col0 + 4) = h1;
;                         if (P) { u32x4 w; w.x = cvtpk(h0[0], h0[1]); w.y = cvtpk(h0[2], h0[3]); w.z = cvtpk(h1[0], h1[1]); w.w = cvtpk(h1[2], h1[3]);
;                             *(u32x4*)(P + (size_t)grow * DM + col0) = w; }
;                         ss += (h0[0] * h0[0] + h0[1] * h0[1]) + (h0[2] * h0[2] + h0[3] * h0[3]) + (h1[0] * h1[0] + h1[1] * h1[1]) + (h1[2] * h1[2] + h1[3] * h1[3]);
;                     }
	v_pk_add_f32 v[94:95], v[94:95], v[216:217]
	v_pk_add_f32 v[96:97], v[96:97], v[218:219]
	v_pk_add_f32 v[90:91], v[90:91], v[220:221]
	v_pk_add_f32 v[92:93], v[92:93], v[222:223]
	v_pk_add_f32 v[86:87], v[86:87], v[224:225]
	v_pk_add_f32 v[88:89], v[88:89], v[226:227]
	v_pk_add_f32 v[82:83], v[82:83], v[228:229]
	v_pk_add_f32 v[84:85], v[84:85], v[230:231]
	global_store_dwordx4 v150, v[94:97], s[44:45]
	global_store_dwordx4 v150, v[90:93], s[44:45] offset:16
	global_store_dwordx4 v150, v[86:89], s[44:45] offset:512
	global_store_dwordx4 v150, v[82:85], s[44:45] offset:528
	v_cvt_pk_bf16_f32 v216, v94, v95
	v_cvt_pk_bf16_f32 v217, v96, v97
	v_cvt_pk_bf16_f32 v218, v90, v91
	v_cvt_pk_bf16_f32 v219, v92, v93
	v_cvt_pk_bf16_f32 v220, v86, v87
	v_cvt_pk_bf16_f32 v221, v88, v89
	v_cvt_pk_bf16_f32 v222, v82, v83
	v_cvt_pk_bf16_f32 v223, v84, v85
	global_store_dwordx4 v151, v[216:219], s[6:7]
	global_store_dwordx4 v151, v[220:223], s[6:7] offset:256
	v_mul_f32_e32 v163, v94, v94
	v_mul_f32_e32 v200, v95, v95
	v_fmac_f32_e32 v163, v96, v96
	v_fmac_f32_e32 v200, v97, v97
	v_fmac_f32_e32 v163, v90, v90
	v_fmac_f32_e32 v200, v91, v91
	v_fmac_f32_e32 v163, v92, v92
	v_fmac_f32_e32 v200, v93, v93
	v_fmac_f32_e32 v163, v86, v86
	v_fmac_f32_e32 v200, v87, v87
	v_fmac_f32_e32 v163, v88, v88
	v_fmac_f32_e32 v200, v89, v89
	v_fmac_f32_e32 v163, v82, v82
	v_fmac_f32_e32 v200, v83, v83
	v_fmac_f32_e32 v163, v84, v84
	v_fmac_f32_e32 v200, v85, v85
	v_add_f32_e32 v82, v163, v200
	s_add_u32 s44, s44, 0x10000
	s_addc_u32 s45, s45, 0
	s_add_u32 s6, s6, 0x8000
	s_addc_u32 s7, s7, 0
	global_load_dwordx4 v[216:219], v150, s[42:43]
	global_load_dwordx4 v[220:223], v150, s[42:43] offset:16
	global_load_dwordx4 v[224:227], v150, s[42:43] offset:512
	global_load_dwordx4 v[228:231], v150, s[42:43] offset:528
	s_waitcnt vmcnt(34)
	v_pk_add_f32 v[78:79], v[78:79], v[142:143]
	v_pk_add_f32 v[80:81], v[80:81], v[144:145]
	v_pk_add_f32 v[74:75], v[74:75], v[146:147]
	v_pk_add_f32 v[76:77], v[76:77], v[148:149]
	v_pk_add_f32 v[70:71], v[70:71], v[158:159]
	v_pk_add_f32 v[72:73], v[72:73], v[160:161]
	v_pk_add_f32 v[66:67], v[66:67], v[204:205]
	v_pk_add_f32 v[68:69], v[68:69], v[206:207]
	global_store_dwordx4 v150, v[78:81], s[44:45]
	global_store_dwordx4 v150, v[74:77], s[44:45] offset:16
	global_store_dwordx4 v150, v[70:73], s[44:45] offset:512
	global_store_dwordx4 v150, v[66:69], s[44:45] offset:528
	v_cvt_pk_bf16_f32 v142, v78, v79
	v_cvt_pk_bf16_f32 v143, v80, v81
	v_cvt_pk_bf16_f32 v144, v74, v75
	v_cvt_pk_bf16_f32 v145, v76, v77
	v_cvt_pk_bf16_f32 v146, v70, v71
	v_cvt_pk_bf16_f32 v147, v72, v73
	v_cvt_pk_bf16_f32 v148, v66, v67
	v_cvt_pk_bf16_f32 v149, v68, v69
	global_store_dwordx4 v151, v[142:145], s[6:7]
	global_store_dwordx4 v151, v[146:149], s[6:7] offset:256
	v_mul_f32_e32 v163, v78, v78
	v_mul_f32_e32 v200, v79, v79
	v_fmac_f32_e32 v163, v80, v80
	v_fmac_f32_e32 v200, v81, v81
	v_fmac_f32_e32 v163, v74, v74
	v_fmac_f32_e32 v200, v75, v75
	v_fmac_f32_e32 v163, v76, v76
	v_fmac_f32_e32 v200, v77, v77
	v_fmac_f32_e32 v163, v70, v70
	v_fmac_f32_e32 v200, v71, v71
	v_fmac_f32_e32 v163, v72, v72
	v_fmac_f32_e32 v200, v73, v73
	v_fmac_f32_e32 v163, v66, v66
	v_fmac_f32_e32 v200, v67, v67
	v_fmac_f32_e32 v163, v68, v68
	v_fmac_f32_e32 v200, v69, v69
	v_add_f32_e32 v66, v163, v200
	s_add_u32 s44, s44, 0x50000
	s_addc_u32 s45, s45, 0
	s_add_u32 s6, s6, 0x28000
	s_addc_u32 s7, s7, 0
	s_waitcnt vmcnt(36)
	v_pk_add_f32 v[62:63], v[62:63], v[232:233]
	v_pk_add_f32 v[64:65], v[64:65], v[234:235]
	v_pk_add_f32 v[58:59], v[58:59], v[236:237]
	v_pk_add_f32 v[60:61], v[60:61], v[238:239]
	v_pk_add_f32 v[54:55], v[54:55], v[240:241]
	v_pk_add_f32 v[56:57], v[56:57], v[242:243]
	v_pk_add_f32 v[50:51], v[50:51], v[248:249]
	v_pk_add_f32 v[52:53], v[52:53], v[250:251]
	global_store_dwordx4 v150, v[62:65], s[44:45]
	global_store_dwordx4 v150, v[58:61], s[44:45] offset:16
	global_store_dwordx4 v150, v[54:57], s[44:45] offset:512
	global_store_dwordx4 v150, v[50:53], s[44:45] offset:528
	v_cvt_pk_bf16_f32 v232, v62, v63
	v_cvt_pk_bf16_f32 v233, v64, v65
	v_cvt_pk_bf16_f32 v234, v58, v59
	v_cvt_pk_bf16_f32 v235, v60, v61
	v_cvt_pk_bf16_f32 v236, v54, v55
	v_cvt_pk_bf16_f32 v237, v56, v57
	v_cvt_pk_bf16_f32 v238, v50, v51
	v_cvt_pk_bf16_f32 v239, v52, v53
	global_store_dwordx4 v151, v[232:235], s[6:7]
	global_store_dwordx4 v151, v[236:239], s[6:7] offset:256
	v_mul_f32_e32 v163, v62, v62
	v_mul_f32_e32 v200, v63, v63
	v_fmac_f32_e32 v163, v64, v64
	v_fmac_f32_e32 v200, v65, v65
	v_fmac_f32_e32 v163, v58, v58
	v_fmac_f32_e32 v200, v59, v59
	v_fmac_f32_e32 v163, v60, v60
	v_fmac_f32_e32 v200, v61, v61
	v_fmac_f32_e32 v163, v54, v54
	v_fmac_f32_e32 v200, v55, v55
	v_fmac_f32_e32 v163, v56, v56
	v_fmac_f32_e32 v200, v57, v57
	v_fmac_f32_e32 v163, v50, v50
	v_fmac_f32_e32 v200, v51, v51
	v_fmac_f32_e32 v163, v52, v52
	v_fmac_f32_e32 v200, v53, v53
	v_add_f32_e32 v50, v163, v200
	s_add_u32 s44, s44, 0x10000
	s_addc_u32 s45, s45, 0
	s_add_u32 s6, s6, 0x8000
	s_addc_u32 s7, s7, 0
	s_waitcnt vmcnt(32)
; __device__ __forceinline__ unsigned cvtpk(float lo, float hi) { f32x2 v = {lo, hi}; bf16x2_t b = __builtin_convertvector(v, bf16x2_t); return __builtin_bit_cast(unsigned, b); }
;     __device__ __forceinline__ void operator()(const f32x4 (&acc)[2][2][4][2], const pg8::Unit& u, int wr, int wc, int fr, int fq) const {
;     ...
; #pragma unroll
;                     for (int bj = 0; bj < 2; ++bj) {
;                         const int col0 = u.pn * 256 + bj * 128 + wc * 32 + 8 * fq;
;                         const f32x4 h0 = *(const f32x4*)(src + col0) + acc[ai][bj][m][0];
;                         const f32x4 h1 = *(const f32x4*)(src + col0 + 4) + acc[ai][bj][m][1];
;                         *(f32x4*)(dst + col0) = h0; *(f32x4*)(dst + col0 + 4) = h1;
;                         if (P) { u32x4 w; w.x = cvtpk(h0[0], h0[1]); w.y = cvtpk(h0[2], h0[3]); w.z = cvtpk(h1[0], h1[1]); w.w = cvtpk(h1[2], h1[3]);
;                             *(u32x4*)(P + (size_t)grow * DM + col0) = w; }
;                         ss += (h0[0] * h0[0] + h0[1] * h0[1]) + (h0[2] * h0[2] + h0[3] * h0[3]) + (h1[0] * h1[0] + h1[1] * h1[1]) + (h1[2] * h1[2] + h1[3] * h1[3]);
;                     }
	v_pk_add_f32 v[46:47], v[46:47], v[168:169]
	v_pk_add_f32 v[48:49], v[48:49], v[170:171]
	v_pk_add_f32 v[42:43], v[42:43], v[172:173]
	v_pk_add_f32 v[44:45], v[44:45], v[174:175]
	v_pk_add_f32 v[38:39], v[38:39], v[176:177]
	v_pk_add_f32 v[40:41], v[40:41], v[178:179]
	v_pk_add_f32 v[34:35], v[34:35], v[180:181]
	v_pk_add_f32 v[36:37], v[36:37], v[182:183]
	global_store_dwordx4 v150, v[46:49], s[44:45]
	global_store_dwordx4 v150, v[42:45], s[44:45] offset:16
	global_store_dwordx4 v150, v[38:41], s[44:45] offset:512
	global_store_dwordx4 v150, v[34:37], s[44:45] offset:528
	v_cvt_pk_bf16_f32 v168, v46, v47
	v_cvt_pk_bf16_f32 v169, v48, v49
	v_cvt_pk_bf16_f32 v170, v42, v43
	v_cvt_pk_bf16_f32 v171, v44, v45
	v_cvt_pk_bf16_f32 v172, v38, v39
	v_cvt_pk_bf16_f32 v173, v40, v41
	v_cvt_pk_bf16_f32 v174, v34, v35
	v_cvt_pk_bf16_f32 v175, v36, v37
	global_store_dwordx4 v151, v[168:171], s[6:7]
	global_store_dwordx4 v151, v[172:175], s[6:7] offset:256
	v_mul_f32_e32 v163, v46, v46
	v_mul_f32_e32 v200, v47, v47
	v_fmac_f32_e32 v163, v48, v48
	v_fmac_f32_e32 v200, v49, v49
	v_fmac_f32_e32 v163, v42, v42
	v_fmac_f32_e32 v200, v43, v43
	v_fmac_f32_e32 v163, v44, v44
	v_fmac_f32_e32 v200, v45, v45
	v_fmac_f32_e32 v163, v38, v38
	v_fmac_f32_e32 v200, v39, v39
	v_fmac_f32_e32 v163, v40, v40
	v_fmac_f32_e32 v200, v41, v41
	v_fmac_f32_e32 v163, v34, v34
	v_fmac_f32_e32 v200, v35, v35
	v_fmac_f32_e32 v163, v36, v36
	v_fmac_f32_e32 v200, v37, v37
	v_add_f32_e32 v34, v163, v200
	s_add_u32 s44, s44, 0x10000
	s_addc_u32 s45, s45, 0
	s_add_u32 s6, s6, 0x8000
	s_addc_u32 s7, s7, 0
	s_waitcnt vmcnt(28)
	v_pk_add_f32 v[28:29], v[28:29], v[184:185]
	v_pk_add_f32 v[30:31], v[30:31], v[186:187]
	v_pk_add_f32 v[24:25], v[24:25], v[188:189]
	v_pk_add_f32 v[26:27], v[26:27], v[190:191]
	v_pk_add_f32 v[20:21], v[20:21], v[192:193]
	v_pk_add_f32 v[22:23], v[22:23], v[194:195]
	v_pk_add_f32 v[16:17], v[16:17], v[196:197]
	v_pk_add_f32 v[18:19], v[18:19], v[198:199]
	global_store_dwordx4 v150, v[28:31], s[44:45]
	global_store_dwordx4 v150, v[24:27], s[44:45] offset:16
	global_store_dwordx4 v150, v[20:23], s[44:45] offset:512
	global_store_dwordx4 v150, v[16:19], s[44:45] offset:528
	v_cvt_pk_bf16_f32 v184, v28, v29
	v_cvt_pk_bf16_f32 v185, v30, v31
	v_cvt_pk_bf16_f32 v186, v24, v25
	v_cvt_pk_bf16_f32 v187, v26, v27
	v_cvt_pk_bf16_f32 v188, v20, v21
	v_cvt_pk_bf16_f32 v189, v22, v23
	v_cvt_pk_bf16_f32 v190, v16, v17
	v_cvt_pk_bf16_f32 v191, v18, v19
	global_store_dwordx4 v151, v[184:187], s[6:7]
	global_store_dwordx4 v151, v[188:191], s[6:7] offset:256
	v_mul_f32_e32 v163, v28, v28
	v_mul_f32_e32 v200, v29, v29
	v_fmac_f32_e32 v163, v30, v30
	v_fmac_f32_e32 v200, v31, v31
	v_fmac_f32_e32 v163, v24, v24
	v_fmac_f32_e32 v200, v25, v25
	v_fmac_f32_e32 v163, v26, v26
	v_fmac_f32_e32 v200, v27, v27
	v_fmac_f32_e32 v163, v20, v20
	v_fmac_f32_e32 v200, v21, v21
	v_fmac_f32_e32 v163, v22, v22
	v_fmac_f32_e32 v200, v23, v23
	v_fmac_f32_e32 v163, v16, v16
	v_fmac_f32_e32 v200, v17, v17
	v_fmac_f32_e32 v163, v18, v18
	v_fmac_f32_e32 v200, v19, v19
	v_add_f32_e32 v16, v163, v200
	s_add_u32 s44, s44, 0x10000
	s_addc_u32 s45, s45, 0
	s_add_u32 s6, s6, 0x8000
	s_addc_u32 s7, s7, 0
	s_waitcnt vmcnt(24)
; __device__ __forceinline__ unsigned cvtpk(float lo, float hi) { f32x2 v = {lo, hi}; bf16x2_t b = __builtin_convertvector(v, bf16x2_t); return __builtin_bit_cast(unsigned, b); }
;     __device__ __forceinline__ void operator()(const f32x4 (&acc)[2][2][4][2], const pg8::Unit& u, int wr, int wc, int fr, int fq) const {
;     ...
; #pragma unroll
;                     for (int bj = 0; bj < 2; ++bj) {
;                         const int col0 = u.pn * 256 + bj * 128 + wc * 32 + 8 * fq;
;                         const f32x4 h0 = *(const f32x4*)(src + col0) + acc[ai][bj][m][0];
;                         const f32x4 h1 = *(const f32x4*)(src + col0 + 4) + acc[ai][bj][m][1];
;                         *(f32x4*)(dst + col0) = h0; *(f32x4*)(dst + col0 + 4) = h1;
;                         if (P) { u32x4 w; w.x = cvtpk(h0[0], h0[1]); w.y = cvtpk(h0[2], h0[3]); w.z = cvtpk(h1[0], h1[1]); w.w = cvtpk(h1[2], h1[3]);
;                             *(u32x4*)(P + (size_t)grow * DM + col0) = w; }
;                         ss += (h0[0] * h0[0] + h0[1] * h0[1]) + (h0[2] * h0[2] + h0[3] * h0[3]) + (h1[0] * h1[0] + h1[1] * h1[1]) + (h1[2] * h1[2] + h1[3] * h1[3]);
;                     }
;                 }
;                 ss += __shfl_xor(ss, 16); ss += __shfl_xor(ss, 32);
;                 if (ok && fq == 0 && rowss_next) atomicAdd(rowss_next + grow, (u64)(ss * SS_SCALE));
	v_pk_add_f32 v[12:13], v[12:13], v[216:217]
	v_pk_add_f32 v[14:15], v[14:15], v[218:219]
	v_pk_add_f32 v[8:9], v[8:9], v[220:221]
	v_pk_add_f32 v[10:11], v[10:11], v[222:223]
	v_pk_add_f32 v[4:5], v[4:5], v[224:225]
	v_pk_add_f32 v[6:7], v[6:7], v[226:227]
	v_pk_add_f32 v[0:1], v[0:1], v[228:229]
	v_pk_add_f32 v[2:3], v[2:3], v[230:231]
	global_store_dwordx4 v150, v[12:15], s[44:45]
	global_store_dwordx4 v150, v[8:11], s[44:45] offset:16
	global_store_dwordx4 v150, v[4:7], s[44:45] offset:512
	global_store_dwordx4 v150, v[0:3], s[44:45] offset:528
	v_cvt_pk_bf16_f32 v216, v12, v13
	v_cvt_pk_bf16_f32 v217, v14, v15
	v_cvt_pk_bf16_f32 v218, v8, v9
	v_cvt_pk_bf16_f32 v219, v10, v11
	v_cvt_pk_bf16_f32 v220, v4, v5
	v_cvt_pk_bf16_f32 v221, v6, v7
	v_cvt_pk_bf16_f32 v222, v0, v1
	v_cvt_pk_bf16_f32 v223, v2, v3
	global_store_dwordx4 v151, v[216:219], s[6:7]
	global_store_dwordx4 v151, v[220:223], s[6:7] offset:256
	v_mul_f32_e32 v163, v12, v12
	v_mul_f32_e32 v200, v13, v13
	v_fmac_f32_e32 v163, v14, v14
	v_fmac_f32_e32 v200, v15, v15
	v_fmac_f32_e32 v163, v8, v8
	v_fmac_f32_e32 v200, v9, v9
	v_fmac_f32_e32 v163, v10, v10
	v_fmac_f32_e32 v200, v11, v11
	v_fmac_f32_e32 v163, v4, v4
	v_fmac_f32_e32 v200, v5, v5
	v_fmac_f32_e32 v163, v6, v6
	v_fmac_f32_e32 v200, v7, v7
	v_fmac_f32_e32 v163, v0, v0
	v_fmac_f32_e32 v200, v1, v1
	v_fmac_f32_e32 v163, v2, v2
	v_fmac_f32_e32 v200, v3, v3
	v_add_f32_e32 v0, v163, v200
	v_mbcnt_lo_u32_b32 v201, -1, 0
	v_mbcnt_hi_u32_b32 v201, -1, v201
	v_xor_b32_e32 v208, 16, v201
	v_xor_b32_e32 v209, 32, v201
	v_lshlrev_b32_e32 v208, 2, v208
	v_lshlrev_b32_e32 v209, 2, v209
	ds_bpermute_b32 v115, v208, v114
	ds_bpermute_b32 v99, v208, v98
	ds_bpermute_b32 v83, v208, v82
	ds_bpermute_b32 v67, v208, v66
	ds_bpermute_b32 v51, v208, v50
	ds_bpermute_b32 v35, v208, v34
	ds_bpermute_b32 v17, v208, v16
	ds_bpermute_b32 v1, v208, v0
	s_waitcnt lgkmcnt(0)
	v_add_f32_e32 v114, v114, v115
	v_add_f32_e32 v98, v98, v99
	v_add_f32_e32 v82, v82, v83
	v_add_f32_e32 v66, v66, v67
	v_add_f32_e32 v50, v50, v51
	v_add_f32_e32 v34, v34, v35
	v_add_f32_e32 v16, v16, v17
	v_add_f32_e32 v0, v0, v1
	ds_bpermute_b32 v115, v209, v114
	ds_bpermute_b32 v99, v209, v98
	ds_bpermute_b32 v83, v209, v82
	ds_bpermute_b32 v67, v209, v66
	ds_bpermute_b32 v51, v209, v50
	ds_bpermute_b32 v35, v209, v34
	ds_bpermute_b32 v17, v209, v16
	ds_bpermute_b32 v1, v209, v0
	s_waitcnt lgkmcnt(0)
	v_add_f32_e32 v114, v114, v115
	v_add_f32_e32 v98, v98, v99
	v_add_f32_e32 v82, v82, v83
	v_add_f32_e32 v66, v66, v67
	v_add_f32_e32 v50, v50, v51
	v_add_f32_e32 v34, v34, v35
	v_add_f32_e32 v16, v16, v17
	v_add_f32_e32 v0, v0, v1
	s_and_saveexec_b64 s[42:43], s[2:3]
	v_mul_f32_e32 v114, 0x49800000, v114
	v_trunc_f32_e32 v114, v114
	v_mul_f32_e32 v115, 0x2f800000, v114
	v_floor_f32_e32 v115, v115
	v_fmac_f32_e32 v114, 0xcf800000, v115
	v_cvt_u32_f32_e32 v116, v114
	v_cvt_u32_f32_e32 v117, v115
	global_atomic_add_x2 v162, v[116:117], s[8:9]
	v_mul_f32_e32 v98, 0x49800000, v98
	v_trunc_f32_e32 v98, v98
	v_mul_f32_e32 v99, 0x2f800000, v98
	v_floor_f32_e32 v99, v99
	v_fmac_f32_e32 v98, 0xcf800000, v99
	v_cvt_u32_f32_e32 v100, v98
	v_cvt_u32_f32_e32 v101, v99
	global_atomic_add_x2 v162, v[100:101], s[8:9] offset:128
	v_mul_f32_e32 v82, 0x49800000, v82
	v_trunc_f32_e32 v82, v82
	v_mul_f32_e32 v83, 0x2f800000, v82
	v_floor_f32_e32 v83, v83
	v_fmac_f32_e32 v82, 0xcf800000, v83
	v_cvt_u32_f32_e32 v84, v82
	v_cvt_u32_f32_e32 v85, v83
	global_atomic_add_x2 v162, v[84:85], s[8:9] offset:256
	v_mul_f32_e32 v66, 0x49800000, v66
	v_trunc_f32_e32 v66, v66
	v_mul_f32_e32 v67, 0x2f800000, v66
	v_floor_f32_e32 v67, v67
	v_fmac_f32_e32 v66, 0xcf800000, v67
	v_cvt_u32_f32_e32 v68, v66
	v_cvt_u32_f32_e32 v69, v67
	global_atomic_add_x2 v162, v[68:69], s[8:9] offset:384
	v_mul_f32_e32 v50, 0x49800000, v50
	v_trunc_f32_e32 v50, v50
	v_mul_f32_e32 v51, 0x2f800000, v50
	v_floor_f32_e32 v51, v51
	v_fmac_f32_e32 v50, 0xcf800000, v51
	v_cvt_u32_f32_e32 v52, v50
	v_cvt_u32_f32_e32 v53, v51
	global_atomic_add_x2 v162, v[52:53], s[8:9] offset:1024
	v_mul_f32_e32 v34, 0x49800000, v34
	v_trunc_f32_e32 v34, v34
	v_mul_f32_e32 v35, 0x2f800000, v34
	v_floor_f32_e32 v35, v35
	v_fmac_f32_e32 v34, 0xcf800000, v35
	v_cvt_u32_f32_e32 v36, v34
	v_cvt_u32_f32_e32 v37, v35
	global_atomic_add_x2 v162, v[36:37], s[8:9] offset:1152
	v_mul_f32_e32 v16, 0x49800000, v16
	v_trunc_f32_e32 v16, v16
	v_mul_f32_e32 v17, 0x2f800000, v16
	v_floor_f32_e32 v17, v17
	v_fmac_f32_e32 v16, 0xcf800000, v17
	v_cvt_u32_f32_e32 v18, v16
	v_cvt_u32_f32_e32 v19, v17
	global_atomic_add_x2 v162, v[18:19], s[8:9] offset:1280
	v_mul_f32_e32 v0, 0x49800000, v0
	v_trunc_f32_e32 v0, v0
	v_mul_f32_e32 v1, 0x2f800000, v0
	v_floor_f32_e32 v1, v1
	v_fmac_f32_e32 v0, 0xcf800000, v1
	v_cvt_u32_f32_e32 v2, v0
	v_cvt_u32_f32_e32 v3, v1
	global_atomic_add_x2 v162, v[2:3], s[8:9] offset:1408
	s_mov_b64 exec, s[42:43]
	s_movk_i32 s75, 0x80
	s_mov_b32 s76, 0x7f807f81
	s_movk_i32 s77, 0x5b
	s_branch .Lepi_done_ao

; __device__ __forceinline__ unsigned cvtpk(float lo, float hi) { f32x2 v = {lo, hi}; bf16x2_t b = __builtin_convertvector(v, bf16x2_t); return __builtin_bit_cast(unsigned, b); }
;     __device__ __forceinline__ void operator()(const f32x4 (&acc)[2][2][4][2], const pg8::Unit& u, int wr, int wc, int fr, int fq) const {
;     ...
;         for (int ai = 0; ai < 2; ++ai)
; #pragma unroll
;             for (int m = 0; m < 4; ++m) {
;                 const int grow = row_base + u.pm * 256 + ai * 128 + wr * 64 + m * 16 + fr;
;                 const bool ok = grow < MREAL;
;                 float ss = 0.f;
;                 if (ok) {
;                     const float* src; float* dst;
;                     if (grow < ROWS_P) { src = srcA + (size_t)grow * DM; dst = dstMain + (size_t)grow * DM; }
;                     else if (grow < ROWS_MAIN) { src = srcB + (size_t)(grow - ROWS_P) * DM; dst = dstMain + (size_t)grow * DM; }
;                     else { const int mr = grow - ROWS_MAIN; src = srcM + (size_t)(mr & meta_mask) * DM; dst = dstM + (size_t)mr * DM; }
; #pragma unroll
;                     for (int bj = 0; bj < 2; ++bj) {
;                         const int col0 = u.pn * 256 + bj * 128 + wc * 32 + 8 * fq;
;                         const f32x4 h0 = *(const f32x4*)(src + col0) + acc[ai][bj][m][0];
;                         const f32x4 h1 = *(const f32x4*)(src + col0 + 4) + acc[ai][bj][m][1];
;                         *(f32x4*)(dst + col0) = h0; *(f32x4*)(dst + col0 + 4) = h1;
;                         if (P) { u32x4 w; w.x = cvtpk(h0[0], h0[1]); w.y = cvtpk(h0[2], h0[3]); w.z = cvtpk(h1[0], h1[1]); w.w = cvtpk(h1[2], h1[3]);
;                             *(u32x4*)(P + (size_t)grow * DM + col0) = w; }
;                         ss += (h0[0] * h0[0] + h0[1] * h0[1]) + (h0[2] * h0[2] + h0[3] * h0[3]) + (h1[0] * h1[0] + h1[1] * h1[1]) + (h1[2] * h1[2] + h1[3] * h1[3]);
;                     }
.LBB0_2135:
	s_lshl_b32 vcc_lo, s8, 8
	s_add_i32 vcc_lo, vcc_lo, s66
	s_cmp_lt_u32 vcc_lo, 0x18000
	s_cbranch_scc0 .Lepi_old_dn
	s_cmp_lg_u64 s[18:19], 0
	s_cbranch_scc0 .Lepi_old_dn
	s_cmp_eq_u64 s[16:17], 0
	s_cbranch_scc0 .Lepi_old_dn
	s_lshl_b32 vcc_hi, s6, 10
	s_lshl_b32 s8, vcc_lo, 3
	s_add_u32 s8, s34, s8
	s_addc_u32 s9, s35, 0
	s_lshl_b32 s6, vcc_lo, 12
	s_add_u32 vcc_hi, vcc_hi, s6
	s_add_u32 s50, s12, vcc_hi
	s_addc_u32 s51, s13, 0
	s_lshr_b32 s6, vcc_hi, 1
	s_add_u32 s6, s30, s6
	s_addc_u32 s7, s31, 0
	s_cmp_lt_u32 vcc_lo, 0x8000
	s_cselect_b32 s48, s12, s36
	s_cselect_b32 s49, s13, s37
	s_cselect_b32 vcc_lo, 0, 0x8000000
	s_sub_u32 vcc_hi, vcc_hi, vcc_lo
	s_add_u32 s48, s48, vcc_hi
	s_addc_u32 s49, s49, 0
	v_lshlrev_b32_e32 v150, 12, v164
	v_lshl_add_u32 v150, v166, 2, v150
	v_lshrrev_b32_e32 v151, 1, v150
	v_lshlrev_b32_e32 v162, 3, v164
	global_load_dwordx4 v[168:171], v150, s[48:49]
	global_load_dwordx4 v[172:175], v150, s[48:49] offset:16
	global_load_dwordx4 v[176:179], v150, s[48:49] offset:512
	global_load_dwordx4 v[180:183], v150, s[48:49] offset:528
	s_add_u32 s48, s48, 0x10000
	s_addc_u32 s49, s49, 0
	global_load_dwordx4 v[184:187], v150, s[48:49]
	global_load_dwordx4 v[188:191], v150, s[48:49] offset:16
	global_load_dwordx4 v[192:195], v150, s[48:49] offset:512
	global_load_dwordx4 v[196:199], v150, s[48:49] offset:528
	s_add_u32 s48, s48, 0x10000
	s_addc_u32 s49, s49, 0
	global_load_dwordx4 v[216:219], v150, s[48:49]
	global_load_dwordx4 v[220:223], v150, s[48:49] offset:16
	global_load_dwordx4 v[224:227], v150, s[48:49] offset:512
	global_load_dwordx4 v[228:231], v150, s[48:49] offset:528
	s_add_u32 s48, s48, 0x10000
	s_addc_u32 s49, s49, 0
	global_load_dwordx4 v[142:145], v150, s[48:49]
	global_load_dwordx4 v[146:149], v150, s[48:49] offset:16
	global_load_dwordx4 v[158:161], v150, s[48:49] offset:512
	global_load_dwordx4 v[204:207], v150, s[48:49] offset:528
	s_add_u32 s48, s48, 0x50000
	s_addc_u32 s49, s49, 0
	global_load_dwordx4 v[232:235], v150, s[48:49]
	global_load_dwordx4 v[236:239], v150, s[48:49] offset:16
	global_load_dwordx4 v[240:243], v150, s[48:49] offset:512
	global_load_dwordx4 v[248:251], v150, s[48:49] offset:528
	s_add_u32 s48, s48, 0x10000
	s_addc_u32 s49, s49, 0
	s_waitcnt vmcnt(16)
	v_pk_add_f32 v[126:127], v[126:127], v[168:169]
	v_pk_add_f32 v[128:129], v[128:129], v[170:171]
	v_pk_add_f32 v[122:123], v[122:123], v[172:173]
	v_pk_add_f32 v[124:125], v[124:125], v[174:175]
	v_pk_add_f32 v[118:119], v[118:119], v[176:177]
	v_pk_add_f32 v[120:121], v[120:121], v[178:179]
	v_pk_add_f32 v[114:115], v[114:115], v[180:181]
	v_pk_add_f32 v[116:117], v[116:117], v[182:183]
	global_store_dwordx4 v150, v[126:129], s[50:51]
	global_store_dwordx4 v150, v[122:125], s[50:51] offset:16
	global_store_dwordx4 v150, v[118:121], s[50:51] offset:512
	global_store_dwordx4 v150, v[114:117], s[50:51] offset:528
	v_cvt_pk_bf16_f32 v168, v126, v127
	v_cvt_pk_bf16_f32 v169, v128, v129
	v_cvt_pk_bf16_f32 v170, v122, v123
	v_cvt_pk_bf16_f32 v171, v124, v125
	v_cvt_pk_bf16_f32 v172, v118, v119
	v_cvt_pk_bf16_f32 v173, v120, v121
	v_cvt_pk_bf16_f32 v174, v114, v115
	v_cvt_pk_bf16_f32 v175, v116, v117
	global_store_dwordx4 v151, v[168:171], s[6:7]
	global_store_dwordx4 v151, v[172:175], s[6:7] offset:256
	v_mul_f32_e32 v163, v126, v126
	v_mul_f32_e32 v200, v127, v127
	v_fmac_f32_e32 v163, v128, v128
	v_fmac_f32_e32 v200, v129, v129
	v_fmac_f32_e32 v163, v122, v122
	v_fmac_f32_e32 v200, v123, v123
	v_fmac_f32_e32 v163, v124, v124
	v_fmac_f32_e32 v200, v125, v125
	v_fmac_f32_e32 v163, v118, v118
	v_fmac_f32_e32 v200, v119, v119
	v_fmac_f32_e32 v163, v120, v120
	v_fmac_f32_e32 v200, v121, v121
	v_fmac_f32_e32 v163, v114, v114
	v_fmac_f32_e32 v200, v115, v115
	v_fmac_f32_e32 v163, v116, v116
	v_fmac_f32_e32 v200, v117, v117
	v_add_f32_e32 v114, v163, v200
	s_add_u32 s50, s50, 0x10000
	s_addc_u32 s51, s51, 0
	s_add_u32 s6, s6, 0x8000
	s_addc_u32 s7, s7, 0
	global_load_dwordx4 v[168:171], v150, s[48:49]
	global_load_dwordx4 v[172:175], v150, s[48:49] offset:16
	global_load_dwordx4 v[176:179], v150, s[48:49] offset:512
	global_load_dwordx4 v[180:183], v150, s[48:49] offset:528
	s_add_u32 s48, s48, 0x10000
	s_addc_u32 s49, s49, 0
	s_waitcnt vmcnt(22)
	v_pk_add_f32 v[110:111], v[110:111], v[184:185]
	v_pk_add_f32 v[112:113], v[112:113], v[186:187]
	v_pk_add_f32 v[106:107], v[106:107], v[188:189]
	v_pk_add_f32 v[108:109], v[108:109], v[190:191]
	v_pk_add_f32 v[102:103], v[102:103], v[192:193]
	v_pk_add_f32 v[104:105], v[104:105], v[194:195]
	v_pk_add_f32 v[98:99], v[98:99], v[196:197]
	v_pk_add_f32 v[100:101], v[100:101], v[198:199]
	global_store_dwordx4 v150, v[110:113], s[50:51]
	global_store_dwordx4 v150, v[106:109], s[50:51] offset:16
	global_store_dwordx4 v150, v[102:105], s[50:51] offset:512
	global_store_dwordx4 v150, v[98:101], s[50:51] offset:528
	v_cvt_pk_bf16_f32 v184, v110, v111
	v_cvt_pk_bf16_f32 v185, v112, v113
	v_cvt_pk_bf16_f32 v186, v106, v107
	v_cvt_pk_bf16_f32 v187, v108, v109
	v_cvt_pk_bf16_f32 v188, v102, v103
	v_cvt_pk_bf16_f32 v189, v104, v105
	v_cvt_pk_bf16_f32 v190, v98, v99
	v_cvt_pk_bf16_f32 v191, v100, v101
	global_store_dwordx4 v151, v[184:187], s[6:7]
	global_store_dwordx4 v151, v[188:191], s[6:7] offset:256
	v_mul_f32_e32 v163, v110, v110
	v_mul_f32_e32 v200, v111, v111
	v_fmac_f32_e32 v163, v112, v112
	v_fmac_f32_e32 v200, v113, v113
	v_fmac_f32_e32 v163, v106, v106
	v_fmac_f32_e32 v200, v107, v107
	v_fmac_f32_e32 v163, v108, v108
	v_fmac_f32_e32 v200, v109, v109
	v_fmac_f32_e32 v163, v102, v102
	v_fmac_f32_e32 v200, v103, v103
	v_fmac_f32_e32 v163, v104, v104
	v_fmac_f32_e32 v200, v105, v105
	v_fmac_f32_e32 v163, v98, v98
	v_fmac_f32_e32 v200, v99, v99
	v_fmac_f32_e32 v163, v100, v100
	v_fmac_f32_e32 v200, v101, v101
	v_add_f32_e32 v98, v163, v200
	s_add_u32 s50, s50, 0x10000
	s_addc_u32 s51, s51, 0
	s_add_u32 s6, s6, 0x8000
	s_addc_u32 s7, s7, 0
	global_load_dwordx4 v[184:187], v150, s[48:49]
	global_load_dwordx4 v[188:191], v150, s[48:49] offset:16
	global_load_dwordx4 v[192:195], v150, s[48:49] offset:512
	global_load_dwordx4 v[196:199], v150, s[48:49] offset:528
	s_add_u32 s48, s48, 0x10000
	s_addc_u32 s49, s49, 0
	s_waitcnt vmcnt(28)
; __device__ __forceinline__ unsigned cvtpk(float lo, float hi) { f32x2 v = {lo, hi}; bf16x2_t b = __builtin_convertvector(v, bf16x2_t); return __builtin_bit_cast(unsigned, b); }
;     __device__ __forceinline__ void operator()(const f32x4 (&acc)[2][2][4][2], const pg8::Unit& u, int wr, int wc, int fr, int fq) const {
;     ...
; #pragma unroll
;                     for (int bj = 0; bj < 2; ++bj) {
;                         const int col0 = u.pn * 256 + bj * 128 + wc * 32 + 8 * fq;
;                         const f32x4 h0 = *(const f32x4*)(src + col0) + acc[ai][bj][m][0];
;                         const f32x4 h1 = *(const f32x4*)(src + col0 + 4) + acc[ai][bj][m][1];
;                         *(f32x4*)(dst + col0) = h0; *(f32x4*)(dst + col0 + 4) = h1;
;                         if (P) { u32x4 w; w.x = cvtpk(h0[0], h0[1]); w.y = cvtpk(h0[2], h0[3]); w.z = cvtpk(h1[0], h1[1]); w.w = cvtpk(h1[2], h1[3]);
;                             *(u32x4*)(P + (size_t)grow * DM + col0) = w; }
;                         ss += (h0[0] * h0[0] + h0[1] * h0[1]) + (h0[2] * h0[2] + h0[3] * h0[3]) + (h1[0] * h1[0] + h1[1] * h1[1]) + (h1[2] * h1[2] + h1[3] * h1[3]);
;                     }
	v_pk_add_f32 v[94:95], v[94:95], v[216:217]
	v_pk_add_f32 v[96:97], v[96:97], v[218:219]
	v_pk_add_f32 v[90:91], v[90:91], v[220:221]
	v_pk_add_f32 v[92:93], v[92:93], v[222:223]
	v_pk_add_f32 v[86:87], v[86:87], v[224:225]
	v_pk_add_f32 v[88:89], v[88:89], v[226:227]
	v_pk_add_f32 v[82:83], v[82:83], v[228:229]
	v_pk_add_f32 v[84:85], v[84:85], v[230:231]
	global_store_dwordx4 v150, v[94:97], s[50:51]
	global_store_dwordx4 v150, v[90:93], s[50:51] offset:16
	global_store_dwordx4 v150, v[86:89], s[50:51] offset:512
	global_store_dwordx4 v150, v[82:85], s[50:51] offset:528
	v_cvt_pk_bf16_f32 v216, v94, v95
	v_cvt_pk_bf16_f32 v217, v96, v97
	v_cvt_pk_bf16_f32 v218, v90, v91
	v_cvt_pk_bf16_f32 v219, v92, v93
	v_cvt_pk_bf16_f32 v220, v86, v87
	v_cvt_pk_bf16_f32 v221, v88, v89
	v_cvt_pk_bf16_f32 v222, v82, v83
	v_cvt_pk_bf16_f32 v223, v84, v85
	global_store_dwordx4 v151, v[216:219], s[6:7]
	global_store_dwordx4 v151, v[220:223], s[6:7] offset:256
	v_mul_f32_e32 v163, v94, v94
	v_mul_f32_e32 v200, v95, v95
	v_fmac_f32_e32 v163, v96, v96
	v_fmac_f32_e32 v200, v97, v97
	v_fmac_f32_e32 v163, v90, v90
	v_fmac_f32_e32 v200, v91, v91
	v_fmac_f32_e32 v163, v92, v92
	v_fmac_f32_e32 v200, v93, v93
	v_fmac_f32_e32 v163, v86, v86
	v_fmac_f32_e32 v200, v87, v87
	v_fmac_f32_e32 v163, v88, v88
	v_fmac_f32_e32 v200, v89, v89
	v_fmac_f32_e32 v163, v82, v82
	v_fmac_f32_e32 v200, v83, v83
	v_fmac_f32_e32 v163, v84, v84
	v_fmac_f32_e32 v200, v85, v85
	v_add_f32_e32 v82, v163, v200
	s_add_u32 s50, s50, 0x10000
	s_addc_u32 s51, s51, 0
	s_add_u32 s6, s6, 0x8000
	s_addc_u32 s7, s7, 0
	global_load_dwordx4 v[216:219], v150, s[48:49]
	global_load_dwordx4 v[220:223], v150, s[48:49] offset:16
	global_load_dwordx4 v[224:227], v150, s[48:49] offset:512
	global_load_dwordx4 v[228:231], v150, s[48:49] offset:528
	s_waitcnt vmcnt(34)
	v_pk_add_f32 v[78:79], v[78:79], v[142:143]
	v_pk_add_f32 v[80:81], v[80:81], v[144:145]
	v_pk_add_f32 v[74:75], v[74:75], v[146:147]
	v_pk_add_f32 v[76:77], v[76:77], v[148:149]
	v_pk_add_f32 v[70:71], v[70:71], v[158:159]
	v_pk_add_f32 v[72:73], v[72:73], v[160:161]
	v_pk_add_f32 v[66:67], v[66:67], v[204:205]
	v_pk_add_f32 v[68:69], v[68:69], v[206:207]
	global_store_dwordx4 v150, v[78:81], s[50:51]
	global_store_dwordx4 v150, v[74:77], s[50:51] offset:16
	global_store_dwordx4 v150, v[70:73], s[50:51] offset:512
	global_store_dwordx4 v150, v[66:69], s[50:51] offset:528
	v_cvt_pk_bf16_f32 v142, v78, v79
	v_cvt_pk_bf16_f32 v143, v80, v81
	v_cvt_pk_bf16_f32 v144, v74, v75
	v_cvt_pk_bf16_f32 v145, v76, v77
	v_cvt_pk_bf16_f32 v146, v70, v71
	v_cvt_pk_bf16_f32 v147, v72, v73
	v_cvt_pk_bf16_f32 v148, v66, v67
	v_cvt_pk_bf16_f32 v149, v68, v69
	global_store_dwordx4 v151, v[142:145], s[6:7]
	global_store_dwordx4 v151, v[146:149], s[6:7] offset:256
	v_mul_f32_e32 v163, v78, v78
	v_mul_f32_e32 v200, v79, v79
	v_fmac_f32_e32 v163, v80, v80
	v_fmac_f32_e32 v200, v81, v81
	v_fmac_f32_e32 v163, v74, v74
	v_fmac_f32_e32 v200, v75, v75
	v_fmac_f32_e32 v163, v76, v76
	v_fmac_f32_e32 v200, v77, v77
	v_fmac_f32_e32 v163, v70, v70
	v_fmac_f32_e32 v200, v71, v71
	v_fmac_f32_e32 v163, v72, v72
	v_fmac_f32_e32 v200, v73, v73
	v_fmac_f32_e32 v163, v66, v66
	v_fmac_f32_e32 v200, v67, v67
	v_fmac_f32_e32 v163, v68, v68
	v_fmac_f32_e32 v200, v69, v69
	v_add_f32_e32 v66, v163, v200
	s_add_u32 s50, s50, 0x50000
	s_addc_u32 s51, s51, 0
	s_add_u32 s6, s6, 0x28000
	s_addc_u32 s7, s7, 0
	s_waitcnt vmcnt(36)
	v_pk_add_f32 v[62:63], v[62:63], v[232:233]
	v_pk_add_f32 v[64:65], v[64:65], v[234:235]
	v_pk_add_f32 v[58:59], v[58:59], v[236:237]
	v_pk_add_f32 v[60:61], v[60:61], v[238:239]
	v_pk_add_f32 v[54:55], v[54:55], v[240:241]
	v_pk_add_f32 v[56:57], v[56:57], v[242:243]
	v_pk_add_f32 v[50:51], v[50:51], v[248:249]
	v_pk_add_f32 v[52:53], v[52:53], v[250:251]
	global_store_dwordx4 v150, v[62:65], s[50:51]
	global_store_dwordx4 v150, v[58:61], s[50:51] offset:16
	global_store_dwordx4 v150, v[54:57], s[50:51] offset:512
	global_store_dwordx4 v150, v[50:53], s[50:51] offset:528
	v_cvt_pk_bf16_f32 v232, v62, v63
	v_cvt_pk_bf16_f32 v233, v64, v65
	v_cvt_pk_bf16_f32 v234, v58, v59
	v_cvt_pk_bf16_f32 v235, v60, v61
	v_cvt_pk_bf16_f32 v236, v54, v55
	v_cvt_pk_bf16_f32 v237, v56, v57
	v_cvt_pk_bf16_f32 v238, v50, v51
	v_cvt_pk_bf16_f32 v239, v52, v53
	global_store_dwordx4 v151, v[232:235], s[6:7]
	global_store_dwordx4 v151, v[236:239], s[6:7] offset:256
	v_mul_f32_e32 v163, v62, v62
	v_mul_f32_e32 v200, v63, v63
	v_fmac_f32_e32 v163, v64, v64
	v_fmac_f32_e32 v200, v65, v65
	v_fmac_f32_e32 v163, v58, v58
	v_fmac_f32_e32 v200, v59, v59
	v_fmac_f32_e32 v163, v60, v60
	v_fmac_f32_e32 v200, v61, v61
	v_fmac_f32_e32 v163, v54, v54
	v_fmac_f32_e32 v200, v55, v55
	v_fmac_f32_e32 v163, v56, v56
	v_fmac_f32_e32 v200, v57, v57
	v_fmac_f32_e32 v163, v50, v50
	v_fmac_f32_e32 v200, v51, v51
	v_fmac_f32_e32 v163, v52, v52
	v_fmac_f32_e32 v200, v53, v53
	v_add_f32_e32 v50, v163, v200
	s_add_u32 s50, s50, 0x10000
	s_addc_u32 s51, s51, 0
	s_add_u32 s6, s6, 0x8000
	s_addc_u32 s7, s7, 0
	s_waitcnt vmcnt(32)
; __device__ __forceinline__ unsigned cvtpk(float lo, float hi) { f32x2 v = {lo, hi}; bf16x2_t b = __builtin_convertvector(v, bf16x2_t); return __builtin_bit_cast(unsigned, b); }
;     __device__ __forceinline__ void operator()(const f32x4 (&acc)[2][2][4][2], const pg8::Unit& u, int wr, int wc, int fr, int fq) const {
;     ...
; #pragma unroll
;                     for (int bj = 0; bj < 2; ++bj) {
;                         const int col0 = u.pn * 256 + bj * 128 + wc * 32 + 8 * fq;
;                         const f32x4 h0 = *(const f32x4*)(src + col0) + acc[ai][bj][m][0];
;                         const f32x4 h1 = *(const f32x4*)(src + col0 + 4) + acc[ai][bj][m][1];
;                         *(f32x4*)(dst + col0) = h0; *(f32x4*)(dst + col0 + 4) = h1;
;                         if (P) { u32x4 w; w.x = cvtpk(h0[0], h0[1]); w.y = cvtpk(h0[2], h0[3]); w.z = cvtpk(h1[0], h1[1]); w.w = cvtpk(h1[2], h1[3]);
;                             *(u32x4*)(P + (size_t)grow * DM + col0) = w; }
;                         ss += (h0[0] * h0[0] + h0[1] * h0[1]) + (h0[2] * h0[2] + h0[3] * h0[3]) + (h1[0] * h1[0] + h1[1] * h1[1]) + (h1[2] * h1[2] + h1[3] * h1[3]);
;                     }
	v_pk_add_f32 v[46:47], v[46:47], v[168:169]
	v_pk_add_f32 v[48:49], v[48:49], v[170:171]
	v_pk_add_f32 v[42:43], v[42:43], v[172:173]
	v_pk_add_f32 v[44:45], v[44:45], v[174:175]
	v_pk_add_f32 v[38:39], v[38:39], v[176:177]
	v_pk_add_f32 v[40:41], v[40:41], v[178:179]
	v_pk_add_f32 v[34:35], v[34:35], v[180:181]
	v_pk_add_f32 v[36:37], v[36:37], v[182:183]
	global_store_dwordx4 v150, v[46:49], s[50:51]
	global_store_dwordx4 v150, v[42:45], s[50:51] offset:16
	global_store_dwordx4 v150, v[38:41], s[50:51] offset:512
	global_store_dwordx4 v150, v[34:37], s[50:51] offset:528
	v_cvt_pk_bf16_f32 v168, v46, v47
	v_cvt_pk_bf16_f32 v169, v48, v49
	v_cvt_pk_bf16_f32 v170, v42, v43
	v_cvt_pk_bf16_f32 v171, v44, v45
	v_cvt_pk_bf16_f32 v172, v38, v39
	v_cvt_pk_bf16_f32 v173, v40, v41
	v_cvt_pk_bf16_f32 v174, v34, v35
	v_cvt_pk_bf16_f32 v175, v36, v37
	global_store_dwordx4 v151, v[168:171], s[6:7]
	global_store_dwordx4 v151, v[172:175], s[6:7] offset:256
	v_mul_f32_e32 v163, v46, v46
	v_mul_f32_e32 v200, v47, v47
	v_fmac_f32_e32 v163, v48, v48
	v_fmac_f32_e32 v200, v49, v49
	v_fmac_f32_e32 v163, v42, v42
	v_fmac_f32_e32 v200, v43, v43
	v_fmac_f32_e32 v163, v44, v44
	v_fmac_f32_e32 v200, v45, v45
	v_fmac_f32_e32 v163, v38, v38
	v_fmac_f32_e32 v200, v39, v39
	v_fmac_f32_e32 v163, v40, v40
	v_fmac_f32_e32 v200, v41, v41
	v_fmac_f32_e32 v163, v34, v34
	v_fmac_f32_e32 v200, v35, v35
	v_fmac_f32_e32 v163, v36, v36
	v_fmac_f32_e32 v200, v37, v37
	v_add_f32_e32 v34, v163, v200
	s_add_u32 s50, s50, 0x10000
	s_addc_u32 s51, s51, 0
	s_add_u32 s6, s6, 0x8000
	s_addc_u32 s7, s7, 0
	s_waitcnt vmcnt(28)
	v_pk_add_f32 v[28:29], v[28:29], v[184:185]
	v_pk_add_f32 v[30:31], v[30:31], v[186:187]
	v_pk_add_f32 v[24:25], v[24:25], v[188:189]
	v_pk_add_f32 v[26:27], v[26:27], v[190:191]
	v_pk_add_f32 v[20:21], v[20:21], v[192:193]
	v_pk_add_f32 v[22:23], v[22:23], v[194:195]
	v_pk_add_f32 v[16:17], v[16:17], v[196:197]
	v_pk_add_f32 v[18:19], v[18:19], v[198:199]
	global_store_dwordx4 v150, v[28:31], s[50:51]
	global_store_dwordx4 v150, v[24:27], s[50:51] offset:16
	global_store_dwordx4 v150, v[20:23], s[50:51] offset:512
	global_store_dwordx4 v150, v[16:19], s[50:51] offset:528
	v_cvt_pk_bf16_f32 v184, v28, v29
	v_cvt_pk_bf16_f32 v185, v30, v31
	v_cvt_pk_bf16_f32 v186, v24, v25
	v_cvt_pk_bf16_f32 v187, v26, v27
	v_cvt_pk_bf16_f32 v188, v20, v21
	v_cvt_pk_bf16_f32 v189, v22, v23
	v_cvt_pk_bf16_f32 v190, v16, v17
	v_cvt_pk_bf16_f32 v191, v18, v19
	global_store_dwordx4 v151, v[184:187], s[6:7]
	global_store_dwordx4 v151, v[188:191], s[6:7] offset:256
	v_mul_f32_e32 v163, v28, v28
	v_mul_f32_e32 v200, v29, v29
	v_fmac_f32_e32 v163, v30, v30
	v_fmac_f32_e32 v200, v31, v31
	v_fmac_f32_e32 v163, v24, v24
	v_fmac_f32_e32 v200, v25, v25
	v_fmac_f32_e32 v163, v26, v26
	v_fmac_f32_e32 v200, v27, v27
	v_fmac_f32_e32 v163, v20, v20
	v_fmac_f32_e32 v200, v21, v21
	v_fmac_f32_e32 v163, v22, v22
	v_fmac_f32_e32 v200, v23, v23
	v_fmac_f32_e32 v163, v16, v16
	v_fmac_f32_e32 v200, v17, v17
	v_fmac_f32_e32 v163, v18, v18
	v_fmac_f32_e32 v200, v19, v19
	v_add_f32_e32 v16, v163, v200
	s_add_u32 s50, s50, 0x10000
	s_addc_u32 s51, s51, 0
	s_add_u32 s6, s6, 0x8000
	s_addc_u32 s7, s7, 0
	s_waitcnt vmcnt(24)
; __device__ __forceinline__ unsigned cvtpk(float lo, float hi) { f32x2 v = {lo, hi}; bf16x2_t b = __builtin_convertvector(v, bf16x2_t); return __builtin_bit_cast(unsigned, b); }
;     __device__ __forceinline__ void operator()(const f32x4 (&acc)[2][2][4][2], const pg8::Unit& u, int wr, int wc, int fr, int fq) const {
;     ...
; #pragma unroll
;                     for (int bj = 0; bj < 2; ++bj) {
;                         const int col0 = u.pn * 256 + bj * 128 + wc * 32 + 8 * fq;
;                         const f32x4 h0 = *(const f32x4*)(src + col0) + acc[ai][bj][m][0];
;                         const f32x4 h1 = *(const f32x4*)(src + col0 + 4) + acc[ai][bj][m][1];
;                         *(f32x4*)(dst + col0) = h0; *(f32x4*)(dst + col0 + 4) = h1;
;                         if (P) { u32x4 w; w.x = cvtpk(h0[0], h0[1]); w.y = cvtpk(h0[2], h0[3]); w.z = cvtpk(h1[0], h1[1]); w.w = cvtpk(h1[2], h1[3]);
;                             *(u32x4*)(P + (size_t)grow * DM + col0) = w; }
;                         ss += (h0[0] * h0[0] + h0[1] * h0[1]) + (h0[2] * h0[2] + h0[3] * h0[3]) + (h1[0] * h1[0] + h1[1] * h1[1]) + (h1[2] * h1[2] + h1[3] * h1[3]);
;                     }
;                 }
;                 ss += __shfl_xor(ss, 16); ss += __shfl_xor(ss, 32);
;                 if (ok && fq == 0 && rowss_next) atomicAdd(rowss_next + grow, (u64)(ss * SS_SCALE));
	v_pk_add_f32 v[12:13], v[12:13], v[216:217]
	v_pk_add_f32 v[14:15], v[14:15], v[218:219]
	v_pk_add_f32 v[8:9], v[8:9], v[220:221]
	v_pk_add_f32 v[10:11], v[10:11], v[222:223]
	v_pk_add_f32 v[4:5], v[4:5], v[224:225]
	v_pk_add_f32 v[6:7], v[6:7], v[226:227]
	v_pk_add_f32 v[0:1], v[0:1], v[228:229]
	v_pk_add_f32 v[2:3], v[2:3], v[230:231]
	global_store_dwordx4 v150, v[12:15], s[50:51]
	global_store_dwordx4 v150, v[8:11], s[50:51] offset:16
	global_store_dwordx4 v150, v[4:7], s[50:51] offset:512
	global_store_dwordx4 v150, v[0:3], s[50:51] offset:528
	v_cvt_pk_bf16_f32 v216, v12, v13
	v_cvt_pk_bf16_f32 v217, v14, v15
	v_cvt_pk_bf16_f32 v218, v8, v9
	v_cvt_pk_bf16_f32 v219, v10, v11
	v_cvt_pk_bf16_f32 v220, v4, v5
	v_cvt_pk_bf16_f32 v221, v6, v7
	v_cvt_pk_bf16_f32 v222, v0, v1
	v_cvt_pk_bf16_f32 v223, v2, v3
	global_store_dwordx4 v151, v[216:219], s[6:7]
	global_store_dwordx4 v151, v[220:223], s[6:7] offset:256
	v_mul_f32_e32 v163, v12, v12
	v_mul_f32_e32 v200, v13, v13
	v_fmac_f32_e32 v163, v14, v14
	v_fmac_f32_e32 v200, v15, v15
	v_fmac_f32_e32 v163, v8, v8
	v_fmac_f32_e32 v200, v9, v9
	v_fmac_f32_e32 v163, v10, v10
	v_fmac_f32_e32 v200, v11, v11
	v_fmac_f32_e32 v163, v4, v4
	v_fmac_f32_e32 v200, v5, v5
	v_fmac_f32_e32 v163, v6, v6
	v_fmac_f32_e32 v200, v7, v7
	v_fmac_f32_e32 v163, v0, v0
	v_fmac_f32_e32 v200, v1, v1
	v_fmac_f32_e32 v163, v2, v2
	v_fmac_f32_e32 v200, v3, v3
	v_add_f32_e32 v0, v163, v200
	v_mbcnt_lo_u32_b32 v201, -1, 0
	v_mbcnt_hi_u32_b32 v201, -1, v201
	v_xor_b32_e32 v208, 16, v201
	v_xor_b32_e32 v209, 32, v201
	v_lshlrev_b32_e32 v208, 2, v208
	v_lshlrev_b32_e32 v209, 2, v209
	ds_bpermute_b32 v115, v208, v114
	ds_bpermute_b32 v99, v208, v98
	ds_bpermute_b32 v83, v208, v82
	ds_bpermute_b32 v67, v208, v66
	ds_bpermute_b32 v51, v208, v50
	ds_bpermute_b32 v35, v208, v34
	ds_bpermute_b32 v17, v208, v16
	ds_bpermute_b32 v1, v208, v0
	s_waitcnt lgkmcnt(0)
	v_add_f32_e32 v114, v114, v115
	v_add_f32_e32 v98, v98, v99
	v_add_f32_e32 v82, v82, v83
	v_add_f32_e32 v66, v66, v67
	v_add_f32_e32 v50, v50, v51
	v_add_f32_e32 v34, v34, v35
	v_add_f32_e32 v16, v16, v17
	v_add_f32_e32 v0, v0, v1
	ds_bpermute_b32 v115, v209, v114
	ds_bpermute_b32 v99, v209, v98
	ds_bpermute_b32 v83, v209, v82
	ds_bpermute_b32 v67, v209, v66
	ds_bpermute_b32 v51, v209, v50
	ds_bpermute_b32 v35, v209, v34
	ds_bpermute_b32 v17, v209, v16
	ds_bpermute_b32 v1, v209, v0
	s_waitcnt lgkmcnt(0)
	v_add_f32_e32 v114, v114, v115
	v_add_f32_e32 v98, v98, v99
	v_add_f32_e32 v82, v82, v83
	v_add_f32_e32 v66, v66, v67
	v_add_f32_e32 v50, v50, v51
	v_add_f32_e32 v34, v34, v35
	v_add_f32_e32 v16, v16, v17
	v_add_f32_e32 v0, v0, v1
	s_and_saveexec_b64 s[48:49], s[2:3]
	v_mul_f32_e32 v114, 0x49800000, v114
	v_trunc_f32_e32 v114, v114
	v_mul_f32_e32 v115, 0x2f800000, v114
	v_floor_f32_e32 v115, v115
	v_fmac_f32_e32 v114, 0xcf800000, v115
	v_cvt_u32_f32_e32 v116, v114
	v_cvt_u32_f32_e32 v117, v115
	global_atomic_add_x2 v162, v[116:117], s[8:9]
	v_mul_f32_e32 v98, 0x49800000, v98
	v_trunc_f32_e32 v98, v98
	v_mul_f32_e32 v99, 0x2f800000, v98
	v_floor_f32_e32 v99, v99
	v_fmac_f32_e32 v98, 0xcf800000, v99
	v_cvt_u32_f32_e32 v100, v98
	v_cvt_u32_f32_e32 v101, v99
	global_atomic_add_x2 v162, v[100:101], s[8:9] offset:128
	v_mul_f32_e32 v82, 0x49800000, v82
	v_trunc_f32_e32 v82, v82
	v_mul_f32_e32 v83, 0x2f800000, v82
	v_floor_f32_e32 v83, v83
	v_fmac_f32_e32 v82, 0xcf800000, v83
	v_cvt_u32_f32_e32 v84, v82
	v_cvt_u32_f32_e32 v85, v83
	global_atomic_add_x2 v162, v[84:85], s[8:9] offset:256
	v_mul_f32_e32 v66, 0x49800000, v66
	v_trunc_f32_e32 v66, v66
	v_mul_f32_e32 v67, 0x2f800000, v66
	v_floor_f32_e32 v67, v67
	v_fmac_f32_e32 v66, 0xcf800000, v67
	v_cvt_u32_f32_e32 v68, v66
	v_cvt_u32_f32_e32 v69, v67
	global_atomic_add_x2 v162, v[68:69], s[8:9] offset:384
	v_mul_f32_e32 v50, 0x49800000, v50
	v_trunc_f32_e32 v50, v50
	v_mul_f32_e32 v51, 0x2f800000, v50
	v_floor_f32_e32 v51, v51
	v_fmac_f32_e32 v50, 0xcf800000, v51
	v_cvt_u32_f32_e32 v52, v50
	v_cvt_u32_f32_e32 v53, v51
	global_atomic_add_x2 v162, v[52:53], s[8:9] offset:1024
	v_mul_f32_e32 v34, 0x49800000, v34
	v_trunc_f32_e32 v34, v34
	v_mul_f32_e32 v35, 0x2f800000, v34
	v_floor_f32_e32 v35, v35
	v_fmac_f32_e32 v34, 0xcf800000, v35
	v_cvt_u32_f32_e32 v36, v34
	v_cvt_u32_f32_e32 v37, v35
	global_atomic_add_x2 v162, v[36:37], s[8:9] offset:1152
	v_mul_f32_e32 v16, 0x49800000, v16
	v_trunc_f32_e32 v16, v16
	v_mul_f32_e32 v17, 0x2f800000, v16
	v_floor_f32_e32 v17, v17
	v_fmac_f32_e32 v16, 0xcf800000, v17
	v_cvt_u32_f32_e32 v18, v16
	v_cvt_u32_f32_e32 v19, v17
	global_atomic_add_x2 v162, v[18:19], s[8:9] offset:1280
	v_mul_f32_e32 v0, 0x49800000, v0
	v_trunc_f32_e32 v0, v0
	v_mul_f32_e32 v1, 0x2f800000, v0
	v_floor_f32_e32 v1, v1
	v_fmac_f32_e32 v0, 0xcf800000, v1
	v_cvt_u32_f32_e32 v2, v0
	v_cvt_u32_f32_e32 v3, v1
	global_atomic_add_x2 v162, v[2:3], s[8:9] offset:1408
	s_mov_b64 exec, s[48:49]
	s_branch .Lepi_done_dn
